# v38 plus GU steady loop: next-tile DMA addresses via SGPR base (4 SALU) instead of eight 64-bit VALU adds
# speedup vs baseline: 1.0025x; 1.0025x over previous
.LBB0_532:
	s_add_u32 s6, s8, 0xfff80080
	s_addc_u32 s7, s9, -1
	s_add_i32 s29, 0, 0x10000
	s_cmp_eq_u32 s28, 28
	s_cselect_b32 s17, s13, s7
	s_cselect_b32 s16, s12, s6
	s_cselect_b32 s7, s15, s27
	s_cselect_b32 s6, s14, s26
	s_add_i32 s53, 0, 0x14000
	ds_read_b128 v[138:141], v240
	ds_read_b128 v[142:145], v240 offset:1024
	ds_read_b128 v[148:151], v240 offset:2048
	ds_read_b128 v[152:155], v240 offset:3072
	ds_read_b128 v[156:159], v240 offset:16384
	ds_read_b128 v[160:163], v240 offset:17408
	ds_read_b128 v[164:167], v240 offset:18432
	ds_read_b128 v[168:171], v240 offset:19456
	s_mov_b32 m0, s66
	ds_read_b128 v[172:175], v146
	ds_read_b128 v[176:179], v146 offset:1024
	ds_read_b128 v[180:183], v146 offset:2048
	ds_read_b128 v[184:187], v146 offset:3072
	ds_read_b128 v[188:191], v146 offset:4096
	ds_read_b128 v[192:195], v146 offset:5120
	ds_read_b128 v[196:199], v146 offset:6144
	ds_read_b128 v[200:203], v146 offset:7168
	global_load_lds_dwordx4 v2, s[8:9]
	s_mov_b32 m0, s67
	v_mov_b32_e32 v133, v3
	global_load_lds_dwordx4 v132, s[8:9]
	s_waitcnt vmcnt(8)
	s_waitcnt lgkmcnt(0)
	s_barrier
	s_setprio 1
	s_waitcnt lgkmcnt(0)
	v_mfma_f32_16x16x32_f16 v[4:7], v[138:141], v[172:175], v[4:7]
	v_mfma_f32_16x16x32_f16 v[4:7], v[142:145], v[176:179], v[4:7]
	v_mfma_f32_16x16x32_f16 v[8:11], v[152:155], v[176:179], v[8:11]
	v_mfma_f32_16x16x32_f16 v[8:11], v[148:151], v[172:175], v[8:11]
	v_mfma_f32_16x16x32_f16 v[16:19], v[148:151], v[180:183], v[16:19]
	v_mfma_f32_16x16x32_f16 v[16:19], v[152:155], v[184:187], v[16:19]
	v_mfma_f32_16x16x32_f16 v[12:15], v[142:145], v[184:187], v[12:15]
	v_mfma_f32_16x16x32_f16 v[12:15], v[138:141], v[180:183], v[12:15]
	v_mfma_f32_16x16x32_f16 v[20:23], v[138:141], v[188:191], v[20:23]
	v_mfma_f32_16x16x32_f16 v[20:23], v[142:145], v[192:195], v[20:23]
	v_mfma_f32_16x16x32_f16 v[24:27], v[152:155], v[192:195], v[24:27]
	v_mfma_f32_16x16x32_f16 v[24:27], v[148:151], v[188:191], v[24:27]
	v_mfma_f32_16x16x32_f16 v[32:35], v[148:151], v[196:199], v[32:35]
	v_mfma_f32_16x16x32_f16 v[32:35], v[152:155], v[200:203], v[32:35]
	v_mfma_f32_16x16x32_f16 v[28:31], v[142:145], v[200:203], v[28:31]
	v_mfma_f32_16x16x32_f16 v[28:31], v[138:141], v[196:199], v[28:31]
	s_setprio 0
	s_setprio 1
	v_mfma_f32_16x16x32_f16 v[36:39], v[156:159], v[172:175], v[36:39]
	v_mfma_f32_16x16x32_f16 v[36:39], v[160:163], v[176:179], v[36:39]
	v_mfma_f32_16x16x32_f16 v[40:43], v[168:171], v[176:179], v[40:43]
	v_mfma_f32_16x16x32_f16 v[40:43], v[164:167], v[172:175], v[40:43]
	v_mfma_f32_16x16x32_f16 v[48:51], v[164:167], v[180:183], v[48:51]
	v_mfma_f32_16x16x32_f16 v[48:51], v[168:171], v[184:187], v[48:51]
	v_mfma_f32_16x16x32_f16 v[44:47], v[160:163], v[184:187], v[44:47]
	v_mfma_f32_16x16x32_f16 v[44:47], v[156:159], v[180:183], v[44:47]
	v_mfma_f32_16x16x32_f16 v[52:55], v[156:159], v[188:191], v[52:55]
	v_mfma_f32_16x16x32_f16 v[52:55], v[160:163], v[192:195], v[52:55]
	v_mfma_f32_16x16x32_f16 v[56:59], v[168:171], v[192:195], v[56:59]
	v_mfma_f32_16x16x32_f16 v[56:59], v[164:167], v[188:191], v[56:59]
	v_mfma_f32_16x16x32_f16 v[64:67], v[164:167], v[196:199], v[64:67]
	v_mfma_f32_16x16x32_f16 v[64:67], v[168:171], v[200:203], v[64:67]
	s_setprio 2
	s_barrier
	v_mfma_f32_16x16x32_f16 v[60:63], v[160:163], v[200:203], v[60:63]
	v_mfma_f32_16x16x32_f16 v[60:63], v[156:159], v[196:199], v[60:63]
	s_setprio 0
	s_add_i32 s29, s29, s38
	s_mov_b32 m0, s29
	ds_read_b128 v[172:175], v146 offset:16384
	ds_read_b128 v[176:179], v146 offset:17408
	ds_read_b128 v[180:183], v146 offset:18432
	ds_read_b128 v[184:187], v146 offset:19456
	ds_read_b128 v[188:191], v146 offset:20480
	ds_read_b128 v[192:195], v146 offset:21504
	ds_read_b128 v[196:199], v146 offset:22528
	ds_read_b128 v[200:203], v146 offset:23552
	global_load_lds_dwordx4 v136, s[6:7]
	s_add_i32 m0, s29, 0x2000
	s_add_u32 s40, s6, 0x80000
	s_addc_u32 s41, s7, 0
	s_add_i32 s29, s53, s38
	global_load_lds_dwordx4 v134, s[6:7]
	s_mov_b32 m0, s29
	v_mov_b32_e32 v137, v3
	global_load_lds_dwordx4 v136, s[40:41]
	s_add_i32 m0, s29, 0x2000
	v_mov_b32_e32 v135, v3
	global_load_lds_dwordx4 v134, s[40:41]
	s_mov_b32 m0, s58
	s_nop 0
	global_load_lds_dwordx4 v2, s[16:17]
	s_mov_b32 m0, s59
	s_nop 0
	global_load_lds_dwordx4 v132, s[16:17]
	s_waitcnt vmcnt(8)
	s_waitcnt lgkmcnt(0)
	s_add_u32 s88, s6, s86
	s_addc_u32 s89, s7, s87
	s_add_u32 s90, s16, s86
	s_addc_u32 s91, s17, s87
	s_barrier
	s_setprio 1
	s_waitcnt lgkmcnt(0)
	v_mfma_f32_16x16x32_f16 v[68:71], v[138:141], v[172:175], v[68:71]
	v_mfma_f32_16x16x32_f16 v[68:71], v[142:145], v[176:179], v[68:71]
	v_mfma_f32_16x16x32_f16 v[72:75], v[152:155], v[176:179], v[72:75]
	v_mfma_f32_16x16x32_f16 v[72:75], v[148:151], v[172:175], v[72:75]
	v_mfma_f32_16x16x32_f16 v[80:83], v[148:151], v[180:183], v[80:83]
	v_mfma_f32_16x16x32_f16 v[80:83], v[152:155], v[184:187], v[80:83]
	v_mfma_f32_16x16x32_f16 v[76:79], v[142:145], v[184:187], v[76:79]
	v_mfma_f32_16x16x32_f16 v[76:79], v[138:141], v[180:183], v[76:79]
	v_mfma_f32_16x16x32_f16 v[84:87], v[138:141], v[188:191], v[84:87]
	v_mfma_f32_16x16x32_f16 v[84:87], v[142:145], v[192:195], v[84:87]
	v_mfma_f32_16x16x32_f16 v[88:91], v[152:155], v[192:195], v[88:91]
	v_mfma_f32_16x16x32_f16 v[88:91], v[148:151], v[188:191], v[88:91]
	v_mfma_f32_16x16x32_f16 v[96:99], v[148:151], v[196:199], v[96:99]
	v_mfma_f32_16x16x32_f16 v[96:99], v[152:155], v[200:203], v[96:99]
	v_mfma_f32_16x16x32_f16 v[92:95], v[142:145], v[200:203], v[92:95]
	v_mfma_f32_16x16x32_f16 v[92:95], v[138:141], v[196:199], v[92:95]
	s_setprio 0
	s_setprio 1
	v_mfma_f32_16x16x32_f16 v[100:103], v[156:159], v[172:175], v[100:103]
	v_mfma_f32_16x16x32_f16 v[100:103], v[160:163], v[176:179], v[100:103]
	v_mfma_f32_16x16x32_f16 v[104:107], v[168:171], v[176:179], v[104:107]
	v_mfma_f32_16x16x32_f16 v[104:107], v[164:167], v[172:175], v[104:107]
	v_mfma_f32_16x16x32_f16 v[112:115], v[164:167], v[180:183], v[112:115]
	v_mfma_f32_16x16x32_f16 v[112:115], v[168:171], v[184:187], v[112:115]
	v_mfma_f32_16x16x32_f16 v[108:111], v[160:163], v[184:187], v[108:111]
	v_mfma_f32_16x16x32_f16 v[108:111], v[156:159], v[180:183], v[108:111]
	v_mfma_f32_16x16x32_f16 v[116:119], v[156:159], v[188:191], v[116:119]
	v_mfma_f32_16x16x32_f16 v[116:119], v[160:163], v[192:195], v[116:119]
	v_mfma_f32_16x16x32_f16 v[120:123], v[168:171], v[192:195], v[120:123]
	v_mfma_f32_16x16x32_f16 v[120:123], v[164:167], v[188:191], v[120:123]
	v_mfma_f32_16x16x32_f16 v[128:131], v[164:167], v[196:199], v[128:131]
	v_mfma_f32_16x16x32_f16 v[128:131], v[168:171], v[200:203], v[128:131]
	s_setprio 2
	s_barrier
	v_mfma_f32_16x16x32_f16 v[124:127], v[160:163], v[200:203], v[124:127]
	v_mfma_f32_16x16x32_f16 v[124:127], v[156:159], v[196:199], v[124:127]
	s_setprio 0
	s_add_i32 s29, 0, 0x18000
	s_add_i32 s40, 0, 0x1c000
	ds_read_b128 v[138:141], v240 offset:32768
	ds_read_b128 v[142:145], v240 offset:33792
	ds_read_b128 v[148:151], v240 offset:34816
	ds_read_b128 v[152:155], v240 offset:35840
	ds_read_b128 v[156:159], v240 offset:49152
	ds_read_b128 v[160:163], v240 offset:50176
	ds_read_b128 v[164:167], v240 offset:51200
	ds_read_b128 v[168:171], v240 offset:52224
	s_add_u32 s16, s16, 0x80000
	s_addc_u32 s17, s17, 0
	s_mov_b32 m0, s60
	ds_read_b128 v[172:175], v146 offset:32768
	ds_read_b128 v[176:179], v146 offset:33792
	ds_read_b128 v[180:183], v146 offset:34816
	ds_read_b128 v[184:187], v146 offset:35840
	ds_read_b128 v[188:191], v146 offset:36864
	ds_read_b128 v[192:195], v146 offset:37888
	ds_read_b128 v[196:199], v146 offset:38912
	ds_read_b128 v[200:203], v146 offset:39936
	global_load_lds_dwordx4 v2, s[16:17]
	s_mov_b32 m0, s61
	s_nop 0
	global_load_lds_dwordx4 v132, s[16:17]
	s_waitcnt vmcnt(8)
	s_waitcnt lgkmcnt(0)
	s_barrier
	s_setprio 1
	s_waitcnt lgkmcnt(0)
	v_mfma_f32_16x16x32_f16 v[4:7], v[138:141], v[172:175], v[4:7]
	v_mfma_f32_16x16x32_f16 v[4:7], v[142:145], v[176:179], v[4:7]
	v_mfma_f32_16x16x32_f16 v[8:11], v[152:155], v[176:179], v[8:11]
	v_mfma_f32_16x16x32_f16 v[8:11], v[148:151], v[172:175], v[8:11]
	v_mfma_f32_16x16x32_f16 v[16:19], v[148:151], v[180:183], v[16:19]
	v_mfma_f32_16x16x32_f16 v[16:19], v[152:155], v[184:187], v[16:19]
	v_mfma_f32_16x16x32_f16 v[12:15], v[142:145], v[184:187], v[12:15]
	v_mfma_f32_16x16x32_f16 v[12:15], v[138:141], v[180:183], v[12:15]
	v_mfma_f32_16x16x32_f16 v[20:23], v[138:141], v[188:191], v[20:23]
	v_mfma_f32_16x16x32_f16 v[20:23], v[142:145], v[192:195], v[20:23]
	v_mfma_f32_16x16x32_f16 v[24:27], v[152:155], v[192:195], v[24:27]
	v_mfma_f32_16x16x32_f16 v[24:27], v[148:151], v[188:191], v[24:27]
	v_mfma_f32_16x16x32_f16 v[32:35], v[148:151], v[196:199], v[32:35]
	v_mfma_f32_16x16x32_f16 v[32:35], v[152:155], v[200:203], v[32:35]
	v_mfma_f32_16x16x32_f16 v[28:31], v[142:145], v[200:203], v[28:31]
	v_mfma_f32_16x16x32_f16 v[28:31], v[138:141], v[196:199], v[28:31]
	s_setprio 0
	s_setprio 1
	v_mfma_f32_16x16x32_f16 v[36:39], v[156:159], v[172:175], v[36:39]
	v_mfma_f32_16x16x32_f16 v[36:39], v[160:163], v[176:179], v[36:39]
	v_mfma_f32_16x16x32_f16 v[40:43], v[168:171], v[176:179], v[40:43]
	v_mfma_f32_16x16x32_f16 v[40:43], v[164:167], v[172:175], v[40:43]
	v_mfma_f32_16x16x32_f16 v[48:51], v[164:167], v[180:183], v[48:51]
	v_mfma_f32_16x16x32_f16 v[48:51], v[168:171], v[184:187], v[48:51]
	v_mfma_f32_16x16x32_f16 v[44:47], v[160:163], v[184:187], v[44:47]
	v_mfma_f32_16x16x32_f16 v[44:47], v[156:159], v[180:183], v[44:47]
	v_mfma_f32_16x16x32_f16 v[52:55], v[156:159], v[188:191], v[52:55]
	v_mfma_f32_16x16x32_f16 v[52:55], v[160:163], v[192:195], v[52:55]
	v_mfma_f32_16x16x32_f16 v[56:59], v[168:171], v[192:195], v[56:59]
	v_mfma_f32_16x16x32_f16 v[56:59], v[164:167], v[188:191], v[56:59]
	v_mfma_f32_16x16x32_f16 v[64:67], v[164:167], v[196:199], v[64:67]
	v_mfma_f32_16x16x32_f16 v[64:67], v[168:171], v[200:203], v[64:67]
	s_setprio 2
	s_barrier
	v_mfma_f32_16x16x32_f16 v[60:63], v[160:163], v[200:203], v[60:63]
	v_mfma_f32_16x16x32_f16 v[60:63], v[156:159], v[196:199], v[60:63]
	s_setprio 0
	s_add_i32 s16, s29, s38
	s_mov_b32 m0, s16
	ds_read_b128 v[172:175], v146 offset:49152
	ds_read_b128 v[176:179], v146 offset:50176
	ds_read_b128 v[180:183], v146 offset:51200
	ds_read_b128 v[184:187], v146 offset:52224
	ds_read_b128 v[188:191], v146 offset:53248
	ds_read_b128 v[192:195], v146 offset:54272
	ds_read_b128 v[196:199], v146 offset:55296
	ds_read_b128 v[200:203], v146 offset:56320
	global_load_lds_dwordx4 v136, s[88:89]
	s_add_i32 m0, s16, 0x2000
	s_add_u32 s6, s6, 0x80080
	s_addc_u32 s7, s7, 0
	s_add_i32 s16, s40, s38
	global_load_lds_dwordx4 v134, s[88:89]
	s_mov_b32 m0, s16
	s_nop 0
	global_load_lds_dwordx4 v136, s[6:7]
	s_add_i32 m0, s16, 0x2000
	s_nop 0
	global_load_lds_dwordx4 v134, s[6:7]
	s_mov_b32 m0, s64
	s_nop 0
	global_load_lds_dwordx4 v2, s[90:91]
	s_mov_b32 m0, s65
	s_nop 0
	global_load_lds_dwordx4 v132, s[90:91]
	s_waitcnt vmcnt(8)
	s_waitcnt lgkmcnt(0)
	s_barrier
	s_setprio 1
	s_waitcnt lgkmcnt(0)
	v_mfma_f32_16x16x32_f16 v[68:71], v[138:141], v[172:175], v[68:71]
	v_mfma_f32_16x16x32_f16 v[68:71], v[142:145], v[176:179], v[68:71]
	v_mfma_f32_16x16x32_f16 v[72:75], v[152:155], v[176:179], v[72:75]
	v_mfma_f32_16x16x32_f16 v[72:75], v[148:151], v[172:175], v[72:75]
	v_mfma_f32_16x16x32_f16 v[80:83], v[148:151], v[180:183], v[80:83]
	v_mfma_f32_16x16x32_f16 v[80:83], v[152:155], v[184:187], v[80:83]
	v_mfma_f32_16x16x32_f16 v[76:79], v[142:145], v[184:187], v[76:79]
	v_mfma_f32_16x16x32_f16 v[76:79], v[138:141], v[180:183], v[76:79]
	v_mfma_f32_16x16x32_f16 v[84:87], v[138:141], v[188:191], v[84:87]
	v_mfma_f32_16x16x32_f16 v[84:87], v[142:145], v[192:195], v[84:87]
	v_mfma_f32_16x16x32_f16 v[88:91], v[152:155], v[192:195], v[88:91]
	v_mfma_f32_16x16x32_f16 v[88:91], v[148:151], v[188:191], v[88:91]
	v_mfma_f32_16x16x32_f16 v[96:99], v[148:151], v[196:199], v[96:99]
	v_mfma_f32_16x16x32_f16 v[96:99], v[152:155], v[200:203], v[96:99]
	v_mfma_f32_16x16x32_f16 v[92:95], v[142:145], v[200:203], v[92:95]
	v_mfma_f32_16x16x32_f16 v[92:95], v[138:141], v[196:199], v[92:95]
	s_setprio 0
	s_setprio 1
	v_mfma_f32_16x16x32_f16 v[100:103], v[156:159], v[172:175], v[100:103]
	v_mfma_f32_16x16x32_f16 v[100:103], v[160:163], v[176:179], v[100:103]
	v_mfma_f32_16x16x32_f16 v[104:107], v[168:171], v[176:179], v[104:107]
	v_mfma_f32_16x16x32_f16 v[104:107], v[164:167], v[172:175], v[104:107]
	v_mfma_f32_16x16x32_f16 v[112:115], v[164:167], v[180:183], v[112:115]
	v_mfma_f32_16x16x32_f16 v[112:115], v[168:171], v[184:187], v[112:115]
	v_mfma_f32_16x16x32_f16 v[108:111], v[160:163], v[184:187], v[108:111]
	v_mfma_f32_16x16x32_f16 v[108:111], v[156:159], v[180:183], v[108:111]
	v_mfma_f32_16x16x32_f16 v[116:119], v[156:159], v[188:191], v[116:119]
	v_mfma_f32_16x16x32_f16 v[116:119], v[160:163], v[192:195], v[116:119]
	v_mfma_f32_16x16x32_f16 v[120:123], v[168:171], v[192:195], v[120:123]
	v_mfma_f32_16x16x32_f16 v[120:123], v[164:167], v[188:191], v[120:123]
	v_mfma_f32_16x16x32_f16 v[128:131], v[164:167], v[196:199], v[128:131]
	v_mfma_f32_16x16x32_f16 v[128:131], v[168:171], v[200:203], v[128:131]
	s_setprio 2
	s_barrier
	v_mfma_f32_16x16x32_f16 v[124:127], v[160:163], v[200:203], v[124:127]
	v_mfma_f32_16x16x32_f16 v[124:127], v[156:159], v[196:199], v[124:127]
	s_setprio 0
	s_add_i32 s28, s28, 2
	s_add_u32 s8, s8, 0x100
	s_addc_u32 s9, s9, 0
	s_add_u32 s26, s26, 0x100
	s_addc_u32 s27, s27, 0
	s_cmp_gt_u32 s28, 29
	s_cbranch_scc0 .LBB0_532
	s_and_b64 vcc, exec, s[50:51]
	s_cbranch_vccz .LBB0_535
	s_barrier
